# phase 0 adaLN GEMV: 16 weight-row loads per trip in flight instead of one serialized round trip per load; NA-local peeled tile bias from LDS table
# speedup vs baseline: 1.0558x; 1.0163x over previous
.LBB0_82:
	v_lshl_add_u64 v[18:19], v[16:17], 0, s[6:7]
	s_mov_b32 s8, 0
	s_mov_b32 s9, 0
	v_lshl_add_u64 v[160:161], v[18:19], 0, s[8:9]
	global_load_dword v192, v[160:161], off
	s_add_u32 s8, s8, 0x6000
	v_lshl_add_u64 v[162:163], v[18:19], 0, s[8:9]
	global_load_dword v193, v[162:163], off
	s_add_u32 s8, s8, 0x6000
	v_lshl_add_u64 v[164:165], v[18:19], 0, s[8:9]
	global_load_dword v194, v[164:165], off
	s_add_u32 s8, s8, 0x6000
	v_lshl_add_u64 v[166:167], v[18:19], 0, s[8:9]
	global_load_dword v195, v[166:167], off
	s_add_u32 s8, s8, 0x6000
	v_lshl_add_u64 v[168:169], v[18:19], 0, s[8:9]
	global_load_dword v196, v[168:169], off
	s_add_u32 s8, s8, 0x6000
	v_lshl_add_u64 v[170:171], v[18:19], 0, s[8:9]
	global_load_dword v197, v[170:171], off
	s_add_u32 s8, s8, 0x6000
	v_lshl_add_u64 v[172:173], v[18:19], 0, s[8:9]
	global_load_dword v198, v[172:173], off
	s_add_u32 s8, s8, 0x6000
	v_lshl_add_u64 v[174:175], v[18:19], 0, s[8:9]
	global_load_dword v199, v[174:175], off
	s_add_u32 s8, s8, 0x6000
	v_lshl_add_u64 v[176:177], v[18:19], 0, s[8:9]
	global_load_dword v200, v[176:177], off
	s_add_u32 s8, s8, 0x6000
	v_lshl_add_u64 v[178:179], v[18:19], 0, s[8:9]
	global_load_dword v201, v[178:179], off
	s_add_u32 s8, s8, 0x6000
	v_lshl_add_u64 v[180:181], v[18:19], 0, s[8:9]
	global_load_dword v202, v[180:181], off
	s_add_u32 s8, s8, 0x6000
	v_lshl_add_u64 v[182:183], v[18:19], 0, s[8:9]
	global_load_dword v203, v[182:183], off
	s_add_u32 s8, s8, 0x6000
	v_lshl_add_u64 v[184:185], v[18:19], 0, s[8:9]
	global_load_dword v204, v[184:185], off
	s_add_u32 s8, s8, 0x6000
	v_lshl_add_u64 v[186:187], v[18:19], 0, s[8:9]
	global_load_dword v205, v[186:187], off
	s_add_u32 s8, s8, 0x6000
	v_lshl_add_u64 v[188:189], v[18:19], 0, s[8:9]
	global_load_dword v206, v[188:189], off
	s_add_u32 s8, s8, 0x6000
	v_lshl_add_u64 v[190:191], v[18:19], 0, s[8:9]
	global_load_dword v207, v[190:191], off
	ds_read_b128 v[80:83], v25
	ds_read_b128 v[84:87], v25 offset:16
	ds_read_b128 v[88:91], v25 offset:32
	ds_read_b128 v[92:95], v25 offset:48
	ds_read_b128 v[96:99], v25 offset:4096
	ds_read_b128 v[100:103], v25 offset:4112
	ds_read_b128 v[104:107], v25 offset:4128
	ds_read_b128 v[108:111], v25 offset:4144
	ds_read_b128 v[112:115], v25 offset:8192
	ds_read_b128 v[116:119], v25 offset:8208
	ds_read_b128 v[120:123], v25 offset:8224
	ds_read_b128 v[124:127], v25 offset:8240
	v_add_u32_e32 v25, 64, v25
	s_add_u32 s6, s6, 0x60000
	s_addc_u32 s7, s7, 0
	s_waitcnt lgkmcnt(0)
	s_waitcnt vmcnt(15)
	v_fmac_f32_e32 v20, v192, v80
	v_fmac_f32_e32 v21, v192, v96
	v_fmac_f32_e32 v24, v192, v112
	s_waitcnt vmcnt(14)
	v_fmac_f32_e32 v20, v193, v81
	v_fmac_f32_e32 v21, v193, v97
	v_fmac_f32_e32 v24, v193, v113
	s_waitcnt vmcnt(13)
	v_fmac_f32_e32 v20, v194, v82
	v_fmac_f32_e32 v21, v194, v98
	v_fmac_f32_e32 v24, v194, v114
	s_waitcnt vmcnt(12)
	v_fmac_f32_e32 v20, v195, v83
	v_fmac_f32_e32 v21, v195, v99
	v_fmac_f32_e32 v24, v195, v115
	s_waitcnt vmcnt(11)
	v_fmac_f32_e32 v20, v196, v84
	v_fmac_f32_e32 v21, v196, v100
	v_fmac_f32_e32 v24, v196, v116
	s_waitcnt vmcnt(10)
	v_fmac_f32_e32 v20, v197, v85
	v_fmac_f32_e32 v21, v197, v101
	v_fmac_f32_e32 v24, v197, v117
	s_waitcnt vmcnt(9)
	v_fmac_f32_e32 v20, v198, v86
	v_fmac_f32_e32 v21, v198, v102
	v_fmac_f32_e32 v24, v198, v118
	s_waitcnt vmcnt(8)
	v_fmac_f32_e32 v20, v199, v87
	v_fmac_f32_e32 v21, v199, v103
	v_fmac_f32_e32 v24, v199, v119
	s_waitcnt vmcnt(7)
	v_fmac_f32_e32 v20, v200, v88
	v_fmac_f32_e32 v21, v200, v104
	v_fmac_f32_e32 v24, v200, v120
	s_waitcnt vmcnt(6)
	v_fmac_f32_e32 v20, v201, v89
	v_fmac_f32_e32 v21, v201, v105
	v_fmac_f32_e32 v24, v201, v121
	s_waitcnt vmcnt(5)
	v_fmac_f32_e32 v20, v202, v90
	v_fmac_f32_e32 v21, v202, v106
	v_fmac_f32_e32 v24, v202, v122
	s_waitcnt vmcnt(4)
	v_fmac_f32_e32 v20, v203, v91
	v_fmac_f32_e32 v21, v203, v107
	v_fmac_f32_e32 v24, v203, v123
	s_waitcnt vmcnt(3)
	v_fmac_f32_e32 v20, v204, v92
	v_fmac_f32_e32 v21, v204, v108
	v_fmac_f32_e32 v24, v204, v124
	s_waitcnt vmcnt(2)
	v_fmac_f32_e32 v20, v205, v93
	v_fmac_f32_e32 v21, v205, v109
	v_fmac_f32_e32 v24, v205, v125
	s_waitcnt vmcnt(1)
	v_fmac_f32_e32 v20, v206, v94
	v_fmac_f32_e32 v21, v206, v110
	v_fmac_f32_e32 v24, v206, v126
	s_waitcnt vmcnt(0)
	v_fmac_f32_e32 v20, v207, v95
	v_fmac_f32_e32 v21, v207, v111
	v_fmac_f32_e32 v24, v207, v127
	s_cmp_eq_u32 s6, 0x600000
	s_cbranch_scc0 .LBB0_82
	s_movk_i32 s5, 0x300
	v_mul_lo_u32 v2, v14, s5
	s_movk_i32 s5, 0xc0
	v_lshl_or_b32 v2, v23, 2, v2
	v_cmp_gt_i32_e32 vcc, s5, v1
	ds_write2st64_b32 v2, v20, v21 offset0:48 offset1:49
	ds_write_b32 v2, v24 offset:12800
	s_waitcnt lgkmcnt(0)
	s_barrier
	s_and_saveexec_b64 s[6:7], vcc
	s_cbranch_execz .LBB0_85
	s_mov_b32 s5, 0x3fffffc0
	v_and_or_b32 v1, v1, s5, v23
	v_lshlrev_b32_e32 v1, 2, v1
	ds_read_b32 v4, v22 offset:12288
	ds_read2st64_b32 v[2:3], v1 offset0:51 offset1:54
	ds_read_b32 v1, v1 offset:14592
	s_mul_i32 s5, s0, 0x1800
	s_add_i32 s5, s5, s4
	v_readlane_b32 s36, v252, 13
	s_waitcnt lgkmcnt(1)
	v_add_f32_e32 v2, v4, v2
	v_add_f32_e32 v2, v2, v3
	s_waitcnt lgkmcnt(0)
	v_add_f32_e32 v1, v2, v1
	v_or_b32_e32 v2, s5, v23
	v_ashrrev_i32_e32 v3, 31, v2
	v_readlane_b32 s40, v252, 17
	v_readlane_b32 s41, v252, 18
	v_readlane_b32 s37, v252, 14
	v_readlane_b32 s38, v252, 15
	v_lshl_add_u64 v[2:3], v[2:3], 2, s[40:41]
	global_load_dword v2, v[2:3], off
	v_readlane_b32 s39, v252, 16
	v_readlane_b32 s42, v252, 19
	v_readlane_b32 s43, v252, 20
	v_readlane_b32 s44, v252, 21
	v_readlane_b32 s45, v252, 22
	v_readlane_b32 s46, v252, 23
	v_readlane_b32 s47, v252, 24
	v_readlane_b32 s48, v252, 25
	v_readlane_b32 s49, v252, 26
	v_readlane_b32 s50, v252, 27
	v_readlane_b32 s51, v252, 28
	s_waitcnt vmcnt(0)
	v_add_f32_e32 v1, v1, v2
	v_mad_u64_u32 v[2:3], s[8:9], s0, 3, v[14:15]
	s_movk_i32 s0, 0x1800
	v_mul_lo_u32 v2, v2, s0
	v_add_u32_e32 v2, s4, v2
	v_or_b32_e32 v2, v2, v23
	v_readlane_b32 s4, v252, 61
	v_ashrrev_i32_e32 v3, 31, v2
	v_readlane_b32 s5, v252, 62
	s_nop 1
	v_lshl_add_u64 v[2:3], v[2:3], 2, s[4:5]
	global_store_dword v[2:3], v1, off

.LBB0_491:
	v_subrev_u32_e32 v42, s3, v80
	v_mul_lo_u32 v42, v42, 31
	s_barrier
	s_waitcnt vmcnt(3)
	ds_write_b128 v94, v[28:31]
	s_waitcnt vmcnt(2)
	ds_write_b128 v95, v[24:27]
	s_waitcnt vmcnt(1)
	ds_write_b128 v92, v[36:39] offset:10240
	s_waitcnt vmcnt(0)
	ds_write_b128 v93, v[32:35] offset:10240
	ds_write_b32 v110, v108 offset:32768
	ds_write_b32 v110, v109 offset:33792
	s_waitcnt lgkmcnt(0)
	s_barrier
	ds_read_b128 v[24:27], v90
	ds_read_b128 v[28:31], v90 offset:64
	s_waitcnt lgkmcnt(1)
	v_mfma_f32_16x16x32_bf16 v[24:27], v[24:27], v[20:23], 0
	ds_read_b128 v[36:39], v90 offset:5184
	s_waitcnt lgkmcnt(1)
	v_mfma_f32_16x16x32_bf16 v[32:35], v[28:31], v[16:19], v[24:27]
	ds_read_b128 v[28:31], v90 offset:2624
	s_nop 3
	ds_read_b128 v[24:27], v90 offset:2560
	s_waitcnt lgkmcnt(0)
	v_mfma_f32_16x16x32_bf16 v[24:27], v[24:27], v[20:23], 0
	v_mfma_f32_16x16x32_bf16 v[28:31], v[28:31], v[16:19], v[24:27]
	s_nop 6
	ds_read_b128 v[24:27], v90 offset:5120
	s_waitcnt lgkmcnt(0)
	v_mfma_f32_16x16x32_bf16 v[24:27], v[24:27], v[20:23], 0
	v_mfma_f32_16x16x32_bf16 v[24:27], v[36:39], v[16:19], v[24:27]
	ds_read_b128 v[36:39], v90 offset:7680
	s_waitcnt lgkmcnt(0)
	v_mfma_f32_16x16x32_bf16 v[20:23], v[36:39], v[20:23], 0
	ds_read_b128 v[36:39], v90 offset:7744
	s_waitcnt lgkmcnt(0)
	v_mfma_f32_16x16x32_bf16 v[16:19], v[36:39], v[16:19], v[20:23]
	s_nop 4
	v_sub_u32_e32 v20, v42, v56
	v_add_u32_e32 v36, 0x145, v20
	v_add_u32_e32 v20, v36, v58
	v_cndmask_b32_e64 v20, v20, 0, s[34:35]
	v_ashrrev_i32_e32 v21, 31, v20
	v_lshlrev_b32_e32 v20, 2, v20
	ds_read_b32 v20, v20 offset:32768
	v_add_u32_e32 v21, v36, v83
	v_cndmask_b32_e64 v22, v21, 0, s[30:31]
	v_ashrrev_i32_e32 v23, 31, v22
	v_lshlrev_b32_e32 v22, 2, v22
	ds_read_b32 v21, v22 offset:32768
	v_add_u32_e32 v22, v36, v82
	v_cndmask_b32_e64 v22, v22, 0, s[28:29]
	v_ashrrev_i32_e32 v23, 31, v22
	v_lshlrev_b32_e32 v22, 2, v22
	ds_read_b32 v22, v22 offset:32768
	v_add_u32_e32 v23, v36, v81
	s_waitcnt lgkmcnt(2)
	v_mul_f32_e32 v20, 0x3fb8aa3b, v20
	v_fmac_f32_e32 v20, 0x3e38aa3b, v32
	v_cndmask_b32_e64 v32, v23, 0, s[26:27]
	v_cndmask_b32_e64 v20, v20, v235, s[34:35]
	s_waitcnt lgkmcnt(1)
	v_mul_f32_e32 v21, 0x3fb8aa3b, v21
	v_fmac_f32_e32 v21, 0x3e38aa3b, v33
	v_ashrrev_i32_e32 v33, 31, v32
	v_lshlrev_b32_e32 v32, 2, v32
	ds_read_b32 v23, v32 offset:32768
	v_add_u32_e32 v32, v36, v79
	v_ashrrev_i32_e32 v33, 31, v32
	v_cndmask_b32_e64 v33, 0, v33, s[24:25]
	v_cndmask_b32_e64 v32, 0, v32, s[24:25]
	v_lshlrev_b32_e32 v32, 2, v32
	ds_read_b32 v32, v32 offset:32768
	s_waitcnt lgkmcnt(2)
	v_mul_f32_e32 v22, 0x3fb8aa3b, v22
	v_cndmask_b32_e64 v21, v21, v235, s[30:31]
	s_mov_b32 s30, 0xf149f2ca
	v_fmac_f32_e32 v22, 0x3e38aa3b, v34
	v_max3_f32 v37, v20, s30, v21
	v_cndmask_b32_e64 v22, v22, v235, s[28:29]
	s_waitcnt lgkmcnt(1)
	v_mul_f32_e32 v23, 0x3fb8aa3b, v23
	v_fmac_f32_e32 v23, 0x3e38aa3b, v35
	v_cndmask_b32_e64 v23, v23, v235, s[26:27]
	v_max3_f32 v34, v37, v22, v23
	s_waitcnt lgkmcnt(0)
	v_mul_f32_e32 v32, 0x3fb8aa3b, v32
	v_fmac_f32_e32 v32, 0x3e38aa3b, v28
	v_cndmask_b32_e64 v28, v235, v32, s[24:25]
	v_add_u32_e32 v32, v36, v78
	v_ashrrev_i32_e32 v33, 31, v32
	v_cndmask_b32_e64 v33, 0, v33, s[22:23]
	v_cndmask_b32_e64 v32, 0, v32, s[22:23]
	v_lshlrev_b32_e32 v32, 2, v32
	ds_read_b32 v32, v32 offset:32768
	s_waitcnt lgkmcnt(0)
	v_mul_f32_e32 v32, 0x3fb8aa3b, v32
	v_fmac_f32_e32 v32, 0x3e38aa3b, v29
	v_cndmask_b32_e64 v29, v235, v32, s[22:23]
	v_add_u32_e32 v32, v36, v77
	v_ashrrev_i32_e32 v33, 31, v32
	v_cndmask_b32_e64 v33, 0, v33, s[20:21]
	v_cndmask_b32_e64 v32, 0, v32, s[20:21]
	v_lshlrev_b32_e32 v32, 2, v32
	ds_read_b32 v32, v32 offset:32768
	v_max3_f32 v34, v34, v28, v29
	s_waitcnt lgkmcnt(0)
	v_mul_f32_e32 v32, 0x3fb8aa3b, v32
	v_fmac_f32_e32 v32, 0x3e38aa3b, v30
	v_cndmask_b32_e64 v30, v235, v32, s[20:21]
	v_add_u32_e32 v32, v36, v76
	v_ashrrev_i32_e32 v33, 31, v32
	v_cndmask_b32_e64 v33, 0, v33, s[18:19]
	v_cndmask_b32_e64 v32, 0, v32, s[18:19]
	v_lshlrev_b32_e32 v32, 2, v32
	ds_read_b32 v32, v32 offset:32768
	s_waitcnt lgkmcnt(0)
	v_mul_f32_e32 v32, 0x3fb8aa3b, v32
	v_fmac_f32_e32 v32, 0x3e38aa3b, v31
	v_cndmask_b32_e64 v31, v235, v32, s[18:19]
	v_add_u32_e32 v32, v36, v75
	v_ashrrev_i32_e32 v33, 31, v32
	v_cndmask_b32_e64 v33, 0, v33, s[16:17]
	v_cndmask_b32_e64 v32, 0, v32, s[16:17]
	v_lshlrev_b32_e32 v32, 2, v32
	ds_read_b32 v32, v32 offset:32768
	v_max3_f32 v34, v34, v30, v31
	s_waitcnt lgkmcnt(0)
	v_mul_f32_e32 v32, 0x3fb8aa3b, v32
	v_fmac_f32_e32 v32, 0x3e38aa3b, v24
	v_cndmask_b32_e64 v24, v235, v32, s[16:17]
	v_add_u32_e32 v32, v36, v74
	v_ashrrev_i32_e32 v33, 31, v32
	v_cndmask_b32_e64 v33, 0, v33, s[14:15]
	v_cndmask_b32_e64 v32, 0, v32, s[14:15]
	v_lshlrev_b32_e32 v32, 2, v32
	ds_read_b32 v32, v32 offset:32768
	s_waitcnt lgkmcnt(0)
	v_mul_f32_e32 v32, 0x3fb8aa3b, v32
	v_fmac_f32_e32 v32, 0x3e38aa3b, v25
	v_cndmask_b32_e64 v25, v235, v32, s[14:15]
	v_add_u32_e32 v32, v36, v73
	v_ashrrev_i32_e32 v33, 31, v32
	v_cndmask_b32_e64 v33, 0, v33, s[12:13]
	v_cndmask_b32_e64 v32, 0, v32, s[12:13]
	v_lshlrev_b32_e32 v32, 2, v32
	ds_read_b32 v32, v32 offset:32768
	v_max3_f32 v34, v34, v24, v25
	s_waitcnt lgkmcnt(0)
	v_mul_f32_e32 v32, 0x3fb8aa3b, v32
	v_fmac_f32_e32 v32, 0x3e38aa3b, v26
	v_cndmask_b32_e64 v26, v235, v32, s[12:13]
	v_add_u32_e32 v32, v36, v72
	v_ashrrev_i32_e32 v33, 31, v32
	v_cndmask_b32_e64 v33, 0, v33, s[10:11]
	v_cndmask_b32_e64 v32, 0, v32, s[10:11]
	v_lshlrev_b32_e32 v32, 2, v32
	ds_read_b32 v32, v32 offset:32768
	s_waitcnt lgkmcnt(0)
	v_mul_f32_e32 v32, 0x3fb8aa3b, v32
	v_fmac_f32_e32 v32, 0x3e38aa3b, v27
	v_cndmask_b32_e64 v27, v235, v32, s[10:11]
	v_add_u32_e32 v32, v36, v71
	v_cndmask_b32_e64 v32, 0, v32, s[8:9]
	v_ashrrev_i32_e32 v33, 31, v32
	v_lshlrev_b32_e32 v32, 2, v32
	ds_read_b32 v32, v32 offset:32768
	v_max3_f32 v34, v34, v26, v27
	s_waitcnt lgkmcnt(0)
	v_mul_f32_e32 v32, 0x3fb8aa3b, v32
	v_fmac_f32_e32 v32, 0x3e38aa3b, v16
	v_cndmask_b32_e64 v16, v235, v32, s[8:9]
	v_add_u32_e32 v32, v36, v70
	v_cndmask_b32_e64 v32, 0, v32, s[6:7]
	v_ashrrev_i32_e32 v33, 31, v32
	v_lshlrev_b32_e32 v32, 2, v32
	ds_read_b32 v32, v32 offset:32768
	s_waitcnt lgkmcnt(0)
	v_mul_f32_e32 v32, 0x3fb8aa3b, v32
	v_fmac_f32_e32 v32, 0x3e38aa3b, v17
	v_cndmask_b32_e64 v17, v235, v32, s[6:7]
	v_add_u32_e32 v32, v36, v69
	v_cndmask_b32_e64 v32, 0, v32, s[4:5]
	v_ashrrev_i32_e32 v33, 31, v32
	v_lshlrev_b32_e32 v32, 2, v32
	ds_read_b32 v32, v32 offset:32768
	v_max3_f32 v34, v34, v16, v17
	s_waitcnt lgkmcnt(0)
	v_mul_f32_e32 v32, 0x3fb8aa3b, v32
	v_fmac_f32_e32 v32, 0x3e38aa3b, v18
	v_cndmask_b32_e64 v18, v235, v32, s[4:5]
	v_add_u32_e32 v32, v36, v68
	v_cndmask_b32_e64 v32, 0, v32, s[40:41]
	v_ashrrev_i32_e32 v33, 31, v32
	v_lshlrev_b32_e32 v32, 2, v32
	ds_read_b32 v32, v32 offset:32768
	s_waitcnt lgkmcnt(0)
	v_mul_f32_e32 v32, 0x3fb8aa3b, v32
	v_fmac_f32_e32 v32, 0x3e38aa3b, v19
	v_cndmask_b32_e64 v19, v235, v32, s[40:41]
	v_max3_f32 v32, v34, v18, v19
	v_mov_b32_e32 v33, v32
	s_nop 1
	v_permlane16_swap_b32_e32 v32, v33
	v_max_f32_e32 v33, v33, v33
	v_max_f32_e32 v32, v32, v32
	v_max_f32_e32 v32, v32, v33
	v_mov_b32_e32 v33, v32
	s_nop 1
	v_permlane32_swap_b32_e32 v32, v33
	v_max3_f32 v32, v65, v32, v33
	v_cmp_gt_f32_e32 vcc, v32, v65
	s_cbranch_vccz .LBB0_493
	v_sub_f32_e32 v33, v65, v32
	v_exp_f32_e32 v34, v33
	s_nop 0
	v_pk_mul_f32 v[14:15], v[14:15], v[34:35] op_sel_hi:[1,0]
	v_pk_mul_f32 v[12:13], v[12:13], v[34:35] op_sel_hi:[1,0]
	v_pk_mul_f32 v[6:7], v[6:7], v[34:35] op_sel_hi:[1,0]
	v_pk_mul_f32 v[4:5], v[4:5], v[34:35] op_sel_hi:[1,0]
	v_pk_mul_f32 v[2:3], v[2:3], v[34:35] op_sel_hi:[1,0]
	v_pk_mul_f32 v[0:1], v[0:1], v[34:35] op_sel_hi:[1,0]
	v_pk_mul_f32 v[10:11], v[10:11], v[34:35] op_sel_hi:[1,0]
	v_pk_mul_f32 v[8:9], v[8:9], v[34:35] op_sel_hi:[1,0]
	v_mul_f32_e32 v59, v59, v34
